# v51: v46 with slower flag polling (s_sleep 4) in the rwkv scan hand-off spin loops
# baseline (speedup 1.0000x reference)
.LBB0_3006:
	s_sleep 4
	s_cbranch_execz .LBB0_3011

.LBB0_3021:
	s_add_i32 s19, s19, 1
	s_cmp_gt_u32 s19, 0x400000
	s_cbranch_scc1 .LBB0_3018
	s_mov_b64 s[4:5], -1
	s_sleep 4
	s_branch .LBB0_3018
